# attention loop first half-step: conditional O rescale + scale/exp2 tail of partialSM moved before the first barrier (only the K/V LDS stores stay between the two barriers)
# baseline (speedup 1.0000x reference)
.Lp1join_fox_1:
	v_cmp_gt_f32_e32 vcc, 1.0, v108
	s_cbranch_vccz .LBB0_651
	s_and_saveexec_b64 s[0:1], s[38:39]
	ds_write_b32 v185, v108 offset:128
	s_or_b64 exec, exec, s[0:1]
	s_waitcnt lgkmcnt(0)
	ds_read_b128 v[88:91], v184 offset:224
	ds_read_b128 v[92:95], v184 offset:192
	ds_read_b128 v[110:113], v184 offset:160
	ds_read_b128 v[202:205], v184 offset:128
	s_waitcnt lgkmcnt(3)
	v_mul_f32 v64, v64, v90
	v_mul_f32 v65, v65, v91
	s_waitcnt lgkmcnt(2)
	v_mul_f32 v60, v60, v94
	v_mul_f32 v61, v61, v95
	s_waitcnt lgkmcnt(1)
	v_mul_f32 v56, v56, v112
	v_mul_f32 v57, v57, v113
	s_waitcnt lgkmcnt(0)
	v_mul_f32 v52, v52, v204
	v_mul_f32 v53, v53, v205
	v_mul_f32 v62, v62, v88
	v_mul_f32 v63, v63, v89
	v_mul_f32 v58, v58, v92
	v_mul_f32 v59, v59, v93
	v_mul_f32 v54, v54, v110
	v_mul_f32 v55, v55, v111
	v_mul_f32 v50, v50, v202
	v_mul_f32 v51, v51, v203
	v_mul_f32 v48, v48, v90
	v_mul_f32 v49, v49, v91
	v_mul_f32 v44, v44, v94
	v_mul_f32 v45, v45, v95
	v_mul_f32 v40, v40, v112
	v_mul_f32 v41, v41, v113
	v_mul_f32 v36, v36, v204
	v_mul_f32 v37, v37, v205
	v_mul_f32 v46, v46, v88
	v_mul_f32 v47, v47, v89
	v_mul_f32 v42, v42, v92
	v_mul_f32 v43, v43, v93
	v_mul_f32 v38, v38, v110
	v_mul_f32 v39, v39, v111
	v_mul_f32 v34, v34, v202
	v_mul_f32 v35, v35, v203
	v_mul_f32 v32, v32, v90
	v_mul_f32 v33, v33, v91
	v_mul_f32 v28, v28, v94
	v_mul_f32 v29, v29, v95
	v_mul_f32 v24, v24, v112
	v_mul_f32 v25, v25, v113
	v_mul_f32 v20, v20, v204
	v_mul_f32 v21, v21, v205
	v_mul_f32 v30, v30, v88
	v_mul_f32 v31, v31, v89
	v_mul_f32 v26, v26, v92
	v_mul_f32 v27, v27, v93
	v_mul_f32 v22, v22, v110
	v_mul_f32 v23, v23, v111
	v_mul_f32 v18, v18, v202
	v_mul_f32 v19, v19, v203
	v_mul_f32 v16, v16, v90
	v_mul_f32 v17, v17, v91
	v_mul_f32 v12, v12, v94
	v_mul_f32 v13, v13, v95
	v_mul_f32 v8, v8, v112
	v_mul_f32 v9, v9, v113
	v_mul_f32 v4, v4, v204
	v_mul_f32 v5, v5, v205
	v_mul_f32 v14, v14, v88
	v_mul_f32 v15, v15, v89
	v_mul_f32 v10, v10, v92
	v_mul_f32 v11, v11, v93
	v_mul_f32 v6, v6, v110
	v_mul_f32 v7, v7, v111
	v_mul_f32 v2, v2, v202
	v_mul_f32 v3, v3, v203
.LBB0_651:
	v_cndmask_b32_e64 v1, v1, v196, s[40:41]
	v_sub_f32_e32 v88, v98, v1
	v_sub_f32_e32 v89, v99, v1
	v_sub_f32_e32 v90, v100, v1
	v_sub_f32_e32 v91, v101, v1
	v_sub_f32_e32 v92, v102, v1
	v_sub_f32_e32 v93, v103, v1
	v_sub_f32_e32 v94, v104, v1
	v_sub_f32_e32 v95, v105, v1
	v_sub_f32_e32 v78, v78, v1
	v_sub_f32_e32 v79, v79, v1
	v_sub_f32_e32 v96, v106, v1
	v_sub_f32_e32 v97, v107, v1
	v_sub_f32_e32 v74, v74, v1
	v_sub_f32_e32 v75, v75, v1
	v_sub_f32_e32 v80, v80, v1
	v_sub_f32_e32 v81, v81, v1
	v_exp_f32_e32 v196, v88
	v_exp_f32_e32 v203, v89
	v_exp_f32_e32 v112, v90
	v_exp_f32_e32 v202, v91
	v_exp_f32_e32 v110, v92
	v_exp_f32_e32 v113, v93
	v_exp_f32_e32 v109, v94
	v_exp_f32_e32 v111, v95
	v_exp_f32_e32 v103, v78
	v_exp_f32_e32 v107, v79
	v_exp_f32_e32 v101, v96
	v_exp_f32_e32 v106, v97
	v_exp_f32_e32 v99, v74
	v_exp_f32_e32 v102, v75
	v_exp_f32_e32 v98, v80
	v_exp_f32_e32 v100, v81
	s_add_i32 s0, s9, 1
	s_cmp_lt_i32 s0, s25
	s_cselect_b64 s[22:23], -1, 0
	s_cmp_ge_i32 s0, s25
	s_barrier
	s_waitcnt vmcnt(1)
	ds_write_b128 v193, v[154:157] offset:32768
	s_waitcnt vmcnt(0)
	ds_write_b128 v193, v[158:161] offset:40960
	ds_write_b128 v194, v[146:149]
	ds_write_b128 v195, v[150:153]
	s_waitcnt lgkmcnt(0)
	s_barrier
	s_cbranch_scc1 .LBB0_653
	v_add_u32_e32 v80, 0x41, v218
	v_mad_i64_i32 v[74:75], s[0:1], v80, s33, v[164:165]
	v_add_u32_e32 v81, 0x61, v218
	v_mad_i64_i32 v[78:79], s[0:1], v81, s33, v[164:165]
	global_load_dwordx4 v[146:149], v[74:75], off
	global_load_dwordx4 v[150:153], v[78:79], off
	v_mad_i64_i32 v[74:75], s[0:1], v80, s33, v[166:167]
	v_mad_i64_i32 v[78:79], s[0:1], v81, s33, v[166:167]
	global_load_dwordx4 v[154:157], v[74:75], off
	global_load_dwordx4 v[158:161], v[78:79], off

.Lp1join_dif_1:
	v_cmp_gt_f32_e32 vcc, 1.0, v181
	s_cbranch_vccz .LBB0_829
	s_and_saveexec_b64 s[0:1], s[38:39]
	ds_write_b32 v155, v181 offset:128
	s_or_b64 exec, exec, s[0:1]
	s_waitcnt lgkmcnt(0)
	ds_read_b128 v[134:137], v154 offset:224
	ds_read_b128 v[138:141], v154 offset:192
	ds_read_b128 v[142:145], v154 offset:160
	ds_read_b128 v[184:187], v154 offset:128
	s_waitcnt lgkmcnt(3)
	v_mul_f32 v64, v64, v136
	v_mul_f32 v65, v65, v137
	s_waitcnt lgkmcnt(2)
	v_mul_f32 v60, v60, v140
	v_mul_f32 v61, v61, v141
	s_waitcnt lgkmcnt(1)
	v_mul_f32 v56, v56, v144
	v_mul_f32 v57, v57, v145
	s_waitcnt lgkmcnt(0)
	v_mul_f32 v52, v52, v186
	v_mul_f32 v53, v53, v187
	v_mul_f32 v62, v62, v134
	v_mul_f32 v63, v63, v135
	v_mul_f32 v58, v58, v138
	v_mul_f32 v59, v59, v139
	v_mul_f32 v54, v54, v142
	v_mul_f32 v55, v55, v143
	v_mul_f32 v50, v50, v184
	v_mul_f32 v51, v51, v185
	v_mul_f32 v48, v48, v136
	v_mul_f32 v49, v49, v137
	v_mul_f32 v44, v44, v140
	v_mul_f32 v45, v45, v141
	v_mul_f32 v40, v40, v144
	v_mul_f32 v41, v41, v145
	v_mul_f32 v36, v36, v186
	v_mul_f32 v37, v37, v187
	v_mul_f32 v46, v46, v134
	v_mul_f32 v47, v47, v135
	v_mul_f32 v42, v42, v138
	v_mul_f32 v43, v43, v139
	v_mul_f32 v38, v38, v142
	v_mul_f32 v39, v39, v143
	v_mul_f32 v34, v34, v184
	v_mul_f32 v35, v35, v185
	v_mul_f32 v32, v32, v136
	v_mul_f32 v33, v33, v137
	v_mul_f32 v28, v28, v140
	v_mul_f32 v29, v29, v141
	v_mul_f32 v24, v24, v144
	v_mul_f32 v25, v25, v145
	v_mul_f32 v20, v20, v186
	v_mul_f32 v21, v21, v187
	v_mul_f32 v30, v30, v134
	v_mul_f32 v31, v31, v135
	v_mul_f32 v26, v26, v138
	v_mul_f32 v27, v27, v139
	v_mul_f32 v22, v22, v142
	v_mul_f32 v23, v23, v143
	v_mul_f32 v18, v18, v184
	v_mul_f32 v19, v19, v185
	v_mul_f32 v16, v16, v136
	v_mul_f32 v17, v17, v137
	v_mul_f32 v12, v12, v140
	v_mul_f32 v13, v13, v141
	v_mul_f32 v8, v8, v144
	v_mul_f32 v9, v9, v145
	v_mul_f32 v4, v4, v186
	v_mul_f32 v5, v5, v187
	v_mul_f32 v14, v14, v134
	v_mul_f32 v15, v15, v135
	v_mul_f32 v10, v10, v138
	v_mul_f32 v11, v11, v139
	v_mul_f32 v6, v6, v142
	v_mul_f32 v7, v7, v143
	v_mul_f32 v2, v2, v184
	v_mul_f32 v3, v3, v185
.LBB0_829:
	v_cndmask_b32_e64 v132, v132, v168, s[40:41]
	v_mul_f32_e32 v183, 0xbe38aa3b, v132
	v_fmamk_f32 v82, v82, 0x3e38aa3b, v183
	v_fmamk_f32 v184, v66, 0x3e38aa3b, v183
	v_fmamk_f32 v66, v83, 0x3e38aa3b, v183
	v_fmamk_f32 v185, v67, 0x3e38aa3b, v183
	v_fmamk_f32 v67, v84, 0x3e38aa3b, v183
	v_fmamk_f32 v186, v68, 0x3e38aa3b, v183
	v_fmamk_f32 v68, v85, 0x3e38aa3b, v183
	v_fmamk_f32 v187, v69, 0x3e38aa3b, v183
	v_fmamk_f32 v69, v86, 0x3e38aa3b, v183
	v_fmamk_f32 v188, v70, 0x3e38aa3b, v183
	v_fmamk_f32 v70, v87, 0x3e38aa3b, v183
	v_fmamk_f32 v189, v71, 0x3e38aa3b, v183
	v_fmamk_f32 v71, v88, 0x3e38aa3b, v183
	v_fmamk_f32 v190, v72, 0x3e38aa3b, v183
	v_fmamk_f32 v72, v89, 0x3e38aa3b, v183
	v_fmamk_f32 v191, v73, 0x3e38aa3b, v183
	v_fmamk_f32 v73, v90, 0x3e38aa3b, v183
	v_fmamk_f32 v192, v74, 0x3e38aa3b, v183
	v_fmamk_f32 v74, v91, 0x3e38aa3b, v183
	v_fmamk_f32 v193, v75, 0x3e38aa3b, v183
	v_fmamk_f32 v75, v92, 0x3e38aa3b, v183
	v_fmamk_f32 v194, v76, 0x3e38aa3b, v183
	v_fmamk_f32 v76, v93, 0x3e38aa3b, v183
	v_fmamk_f32 v195, v77, 0x3e38aa3b, v183
	v_fmamk_f32 v77, v94, 0x3e38aa3b, v183
	v_fmamk_f32 v196, v78, 0x3e38aa3b, v183
	v_fmamk_f32 v78, v95, 0x3e38aa3b, v183
	v_fmamk_f32 v83, v96, 0x3e38aa3b, v183
	v_fmamk_f32 v84, v97, 0x3e38aa3b, v183
	v_exp_f32_e32 v146, v82
	v_exp_f32_e32 v168, v66
	v_exp_f32_e32 v144, v67
	v_exp_f32_e32 v147, v68
	v_exp_f32_e32 v142, v69
	v_exp_f32_e32 v145, v70
	v_exp_f32_e32 v141, v71
	v_exp_f32_e32 v143, v72
	v_exp_f32_e32 v138, v73
	v_exp_f32_e32 v140, v74
	v_exp_f32_e32 v136, v75
	v_exp_f32_e32 v139, v76
	v_exp_f32_e32 v134, v77
	v_exp_f32_e32 v137, v78
	v_exp_f32_e32 v133, v83
	v_exp_f32_e32 v135, v84
	s_add_i32 s0, s8, 1
	s_cmp_lt_i32 s0, s27
	v_fmamk_f32 v197, v79, 0x3e38aa3b, v183
	v_fmamk_f32 v198, v80, 0x3e38aa3b, v183
	v_fmac_f32_e32 v183, 0x3e38aa3b, v81
	s_cselect_b64 s[22:23], -1, 0
	s_cmp_ge_i32 s0, s27
	s_barrier
	s_waitcnt vmcnt(2)
	ds_write_b128 v164, v[122:125] offset:32768
	s_waitcnt vmcnt(0)
	ds_write_b128 v164, v[126:129] offset:40960
	ds_write_b128 v165, v[114:117]
	ds_write_b128 v166, v[118:121]
	s_waitcnt lgkmcnt(0)
	s_barrier
	s_cbranch_scc1 .LBB0_831
	v_add_u32_e32 v66, 0x41, v182
	v_mad_i64_i32 v[66:67], s[0:1], v66, s33, v[130:131]
	v_add_u32_e32 v68, 0x61, v182
	v_mad_i64_i32 v[68:69], s[0:1], v68, s33, v[130:131]
	global_load_dwordx4 v[114:117], v[66:67], off offset:2048
	global_load_dwordx4 v[122:125], v[66:67], off offset:1024
	global_load_dwordx4 v[118:121], v[68:69], off offset:2048
	global_load_dwordx4 v[126:129], v[68:69], off offset:1024
